# up GEMM tile order uses row-tile groups of 2 instead of 8
# speedup vs baseline: 1.0127x; 1.0061x over previous
.LBB0_1652:
	s_cmp_lt_i32 s56, 9
	s_cselect_b64 s[0:1], -1, 0
	s_and_b64 s[4:5], s[0:1], s[4:5]
	s_andn2_b64 vcc, exec, s[4:5]
	s_cbranch_vccnz .LBB0_1669
	s_cmpk_gt_i32 s2, 0x41f
	v_readfirstlane_b32 s1, v166
	s_cbranch_scc1 .LBB0_1669
	s_waitcnt vmcnt(0)
	v_lshrrev_b32_e32 v0, 5, v166
	v_and_b32_e32 v1, 4, v0
	v_lshrrev_b32_e32 v0, 1, v166
	v_bfe_u32 v2, v166, 2, 2
	v_and_b32_e32 v0, 24, v0
	v_lshlrev_b32_e32 v3, 4, v166
	v_or3_b32 v2, v1, v2, v0
	v_add_u32_e32 v1, 0x2000, v3
	v_lshrrev_b32_e32 v4, 7, v1
	s_movk_i32 s0, 0xe0
	v_and_b32_e32 v6, 32, v166
	s_add_u32 s3, s94, 0x8b00000
	v_and_or_b32 v5, v4, s0, v2
	v_bitop3_b32 v10, v3, v6, 48 bitop3:0x6c
	v_and_b32_e32 v11, 64, v166
	v_bfe_u32 v12, v166, 2, 4
	s_movk_i32 s0, 0xf0
	s_addc_u32 s42, s95, 0
	v_or_b32_e32 v3, v10, v11
	v_and_or_b32 v4, v4, s0, v12
	s_add_u32 s43, s94, 0x2700000
	v_lshl_or_b32 v130, v4, 12, v3
	v_lshrrev_b32_e32 v4, 3, v166
	s_movk_i32 s0, 0x60
	s_addc_u32 s44, s95, 0
	v_and_or_b32 v2, v4, s0, v2
	s_movk_i32 s0, 0x70
	s_ashr_i32 s46, s2, 31
	v_lshl_or_b32 v132, v2, 12, v3
	v_and_or_b32 v2, v4, s0, v12
	s_lshr_b32 s0, s46, 29
	s_add_i32 s0, s2, s0
	s_lshr_b32 s12, s1, 6
	s_ashr_i32 s7, s0, 3
	s_and_b32 s0, s0, -8
	s_lshr_b32 s6, s1, 8
	s_lshl_b32 s45, s12, 10
	s_sub_i32 s0, s2, s0
	s_cmp_lt_i32 s0, 0
	s_movk_i32 s47, 0x85
	s_cselect_b32 s8, s47, 0x84
	s_mul_i32 s0, s0, s8
	s_add_i32 s0, s0, s7
	s_ashr_i32 s7, s0, 31
	s_lshr_b32 s7, s7, 26
	s_add_i32 s7, s0, s7
	s_ashr_i32 s8, s7, 6
	s_lshl_b32 s10, s8, 1
	s_sub_i32 s8, 33, s10
	s_min_u32 s11, s8, 2
	s_and_b32 s7, s7, 0xffffffc0
	v_lshl_or_b32 v128, v5, 12, v3
	s_sub_i32 s7, s0, s7
	v_cvt_f32_ubyte0_e32 v5, s11
	v_cvt_f32_i32_e32 v4, s7
	v_rcp_iflag_f32_e32 v6, v5
	v_lshl_or_b32 v134, v2, 12, v3
	s_ashr_i32 s0, s7, 30
	s_or_b32 s0, s0, 1
	v_mul_f32_e32 v2, v4, v6
	v_trunc_f32_e32 v2, v2
	v_fma_f32 v3, -v2, v5, v4
	v_cvt_i32_f32_e32 v2, v2
	v_cmp_ge_f32_e64 s[8:9], |v3|, v5
	s_and_b64 s[8:9], s[8:9], exec
	s_cselect_b32 s0, s0, 0
	v_readfirstlane_b32 s8, v2
	s_add_i32 s0, s8, s0
	s_mul_i32 s8, s0, s11
	s_sub_i32 s7, s7, s8
	s_sext_i32_i16 s7, s7
	s_add_i32 s34, s10, s7
	s_ashr_i32 s35, s34, 31
	s_bfe_i64 s[10:11], s[0:1], 0x100000
	s_lshl_b64 s[8:9], s[34:35], 20
	s_lshl_b64 s[10:11], s[10:11], 20
	s_add_u32 s38, s43, s10
	s_addc_u32 s39, s44, s11
	s_add_i32 s48, s45, 0
	s_add_i32 m0, s48, 0x10000
	v_mov_b32_e32 v137, 0
	global_load_lds_dwordx4 v132, s[38:39]
	s_add_i32 m0, s48, 0x12000
	s_add_u32 s10, s38, 0x80000
	global_load_lds_dwordx4 v128, s[38:39]
	s_addc_u32 s11, s39, 0
	s_add_i32 m0, s48, 0x14000
	v_mov_b32_e32 v133, v137
	global_load_lds_dwordx4 v132, s[10:11]
	s_add_i32 m0, s48, 0x16000
	s_add_u32 s36, s3, s8
	s_addc_u32 s37, s42, s9
	s_add_i32 s49, s48, 0x2000
	global_load_lds_dwordx4 v128, s[10:11]
	s_mov_b32 m0, s48
	s_add_u32 s8, s36, 0x80000
	global_load_lds_dwordx4 v134, s[36:37]
	s_mov_b32 m0, s49
	s_addc_u32 s9, s37, 0
	s_add_i32 s50, s48, 0x4000
	global_load_lds_dwordx4 v130, s[36:37]
	s_mov_b32 m0, s50
	s_add_i32 s51, s48, 0x6000
	global_load_lds_dwordx4 v134, s[8:9]
	s_mov_b32 m0, s51
	v_mov_b32_e32 v129, v137
	global_load_lds_dwordx4 v130, s[8:9]
	v_mov_b32_e32 v135, v137
	v_mov_b32_e32 v131, v137
	s_cmp_eq_u32 s6, 1
	s_mov_b32 s7, 0
	v_lshl_add_u64 v[8:9], s[38:39], 0, v[132:133]
	v_lshl_add_u64 v[6:7], s[38:39], 0, v[128:129]
	v_lshl_add_u64 v[2:3], s[36:37], 0, v[134:135]
	s_cselect_b64 s[8:9], -1, 0
	s_cmp_lg_u32 s6, 1
	v_lshl_add_u64 v[4:5], s[36:37], 0, v[130:131]
	s_cbranch_scc1 .LBB0_1656
	s_barrier

.LBB0_1659:
	s_add_i32 s63, s63, 1
	s_mul_i32 s0, s63, s54
	s_mul_hi_u32 s1, s63, s33
	s_add_i32 s1, s1, s0
	s_mul_i32 s0, s63, s33
	s_add_u32 s28, s0, s2
	s_addc_u32 s29, s1, s46
	v_cmp_gt_i64_e32 vcc, s[28:29], v[144:145]
	v_cmp_lt_i64_e64 s[0:1], s[28:29], v[142:143]
	s_cbranch_vccnz .LBB0_1661
	s_ashr_i32 s24, s28, 31
	s_lshr_b32 s24, s24, 29
	s_add_i32 s24, s28, s24
	s_ashr_i32 s25, s24, 3
	s_and_b32 s24, s24, -8
	s_sub_i32 s24, s28, s24
	s_cmp_lt_i32 s24, 0
	s_cselect_b32 s26, s47, 0x84
	s_mul_i32 s24, s24, s26
	s_add_i32 s24, s24, s25
	s_ashr_i32 s25, s24, 31
	s_lshr_b32 s25, s25, 26
	s_add_i32 s25, s24, s25
	s_ashr_i32 s26, s25, 6
	s_lshl_b32 s26, s26, 1
	s_sub_i32 s27, 33, s26
	s_min_i32 s27, s27, 2
	s_abs_i32 s28, s27
	v_cvt_f32_u32_e32 v0, s28
	s_sub_i32 s30, 0, s28
	s_and_b32 s25, s25, 0xffffffc0
	s_sub_i32 s25, s24, s25
	v_rcp_iflag_f32_e32 v0, v0
	s_abs_i32 s24, s25
	s_xor_b32 s29, s25, s27
	s_ashr_i32 s29, s29, 31
	v_mul_f32_e32 v0, 0x4f7ffffe, v0
	v_cvt_u32_f32_e32 v0, v0
	s_nop 0
	v_readfirstlane_b32 s31, v0
	s_mul_i32 s30, s30, s31
	s_mul_hi_u32 s30, s31, s30
	s_add_i32 s31, s31, s30
	s_mul_hi_u32 s30, s24, s31
	s_mul_i32 s31, s30, s28
	s_sub_i32 s24, s24, s31
	s_add_i32 s40, s30, 1
	s_sub_i32 s31, s24, s28
	s_cmp_ge_u32 s24, s28
	s_cselect_b32 s30, s40, s30
	s_cselect_b32 s24, s31, s24
	s_add_i32 s31, s30, 1
	s_cmp_ge_u32 s24, s28
	s_cselect_b32 s24, s31, s30
	s_xor_b32 s24, s24, s29
	s_sub_i32 s24, s24, s29
	s_mul_i32 s27, s24, s27
	s_sub_i32 s25, s25, s27
	s_add_i32 s26, s26, s25
